# a19 + attention epilogue: lanes i/i+32 exchange 8-byte chunks via v_permlane32_swap so each lane stores 4 dwordx4 instead of 8 dwordx2 (same values)
# speedup vs baseline: 1.0055x; 1.0055x over previous
.LBB0_592:
	v_add_f32_e32 v32, v32, v33
	v_div_scale_f32 v33, s[8:9], v32, v32, 1.0
	v_rcp_f32_e32 v34, v33
	v_div_scale_f32 v35, vcc, 1.0, v32, 1.0
	s_ashr_i32 s8, s38, 3
	v_fma_f32 v36, -v33, v34, 1.0
	v_fmac_f32_e32 v34, v36, v34
	v_mul_f32_e32 v36, v35, v34
	v_fma_f32 v37, -v33, v36, v35
	v_fmac_f32_e32 v36, v37, v34
	v_fma_f32 v33, -v33, v36, v35
	v_div_fmas_f32 v33, v33, v34, v36
	s_ashr_i32 s9, s8, 31
	v_div_fixup_f32 v32, v33, v32, 1.0
	s_lshl_b64 s[8:9], s[8:9], 13
	v_mov_b32_e32 v33, s58
	v_or3_b32 v35, s9, v169, 0
	v_or3_b32 v34, s8, v168, v33
	v_lshl_add_u64 v[34:35], v[34:35], 0, v[170:171]
	v_lshlrev_b64 v[34:35], 10, v[34:35]
	s_lshl_b32 s8, s38, 7
	v_lshl_add_u64 v[34:35], s[20:21], 0, v[34:35]
	s_and_b32 s22, s8, 0x380
	v_lshl_add_u64 v[34:35], v[34:35], 0, s[22:23]
	v_lshlrev_b32_e32 v168, 3, v172
	v_pk_mul_f32 v[16:17], v[16:17], v[32:33] op_sel_hi:[1,0]
	v_pk_mul_f32 v[18:19], v[18:19], v[32:33] op_sel_hi:[1,0]
	v_pk_mul_f32 v[20:21], v[20:21], v[32:33] op_sel_hi:[1,0]
	v_pk_mul_f32 v[22:23], v[22:23], v[32:33] op_sel_hi:[1,0]
	v_pk_mul_f32 v[24:25], v[24:25], v[32:33] op_sel_hi:[1,0]
	v_pk_mul_f32 v[26:27], v[26:27], v[32:33] op_sel_hi:[1,0]
	v_pk_mul_f32 v[28:29], v[28:29], v[32:33] op_sel_hi:[1,0]
	v_pk_mul_f32 v[30:31], v[30:31], v[32:33] op_sel_hi:[1,0]
	v_pk_mul_f32 v[0:1], v[0:1], v[32:33] op_sel_hi:[1,0]
	v_pk_mul_f32 v[2:3], v[2:3], v[32:33] op_sel_hi:[1,0]
	v_pk_mul_f32 v[4:5], v[4:5], v[32:33] op_sel_hi:[1,0]
	v_pk_mul_f32 v[6:7], v[6:7], v[32:33] op_sel_hi:[1,0]
	v_pk_mul_f32 v[8:9], v[8:9], v[32:33] op_sel_hi:[1,0]
	v_pk_mul_f32 v[10:11], v[10:11], v[32:33] op_sel_hi:[1,0]
	v_pk_mul_f32 v[12:13], v[12:13], v[32:33] op_sel_hi:[1,0]
	v_pk_mul_f32 v[14:15], v[14:15], v[32:33] op_sel_hi:[1,0]
	v_lshl_add_u64 v[34:35], v[34:35], 0, v[168:169]
	v_lshl_add_u64 v[34:35], v[34:35], 0, v[168:169]
	v_cvt_pk_bf16_f32 v16, v16, v17
	v_cvt_pk_bf16_f32 v17, v18, v19
	v_cvt_pk_bf16_f32 v18, v20, v21
	v_cvt_pk_bf16_f32 v19, v22, v23
	v_cvt_pk_bf16_f32 v20, v24, v25
	v_cvt_pk_bf16_f32 v21, v26, v27
	v_cvt_pk_bf16_f32 v22, v28, v29
	v_cvt_pk_bf16_f32 v23, v30, v31
	v_cvt_pk_bf16_f32 v0, v0, v1
	v_cvt_pk_bf16_f32 v1, v2, v3
	v_cvt_pk_bf16_f32 v2, v4, v5
	v_cvt_pk_bf16_f32 v3, v6, v7
	v_cvt_pk_bf16_f32 v4, v8, v9
	v_cvt_pk_bf16_f32 v5, v10, v11
	v_cvt_pk_bf16_f32 v6, v12, v13
	v_cvt_pk_bf16_f32 v7, v14, v15
	s_nop 1
	v_permlane32_swap_b32_e32 v16, v18
	v_permlane32_swap_b32_e32 v17, v19
	v_permlane32_swap_b32_e32 v20, v22
	v_permlane32_swap_b32_e32 v21, v23
	v_permlane32_swap_b32_e32 v0, v2
	v_permlane32_swap_b32_e32 v1, v3
	v_permlane32_swap_b32_e32 v4, v6
	v_permlane32_swap_b32_e32 v5, v7
	s_add_i32 s57, s57, s28
	s_cmpk_gt_i32 s57, 0x1ff
	global_store_dwordx4 v[34:35], v[16:19], off
	global_store_dwordx4 v[34:35], v[20:23], off offset:32
	global_store_dwordx4 v[34:35], v[0:3], off offset:64
	global_store_dwordx4 v[34:35], v[4:7], off offset:96
	s_cbranch_scc1 .LBB0_646
